# phase0 rebalance parameter: mod_unit workgroups keep 4 (instead of 5) of their 13 transpose items
# baseline (speedup 1.0000x reference)
.LBB0_69:
	s_add_i32 s24, s19, s92
	s_add_i32 s101, s33, 0x800
	s_cmp_lt_u32 s33, 0x60
	s_cselect_b32 s101, s101, 0x1a7f
	s_cmp_lg_u32 s100, 0
	s_cselect_b32 s101, -1, s101
	s_mov_b32 s98, 0
	s_cmp_le_i32 s24, s101
	s_cbranch_scc1 .Lp0_join
	s_mov_b32 s98, 1
	s_movk_i32 s24, 0x7fff
	s_cmp_lt_u32 s33, 0x60
	s_cbranch_scc1 .Lp0_join
	s_sub_u32 s99, s33, 0x60
	s_mul_i32 s101, s100, 0x1a0
	s_add_u32 s99, s99, s101
	s_add_u32 s100, s100, 1
	s_cmp_ge_u32 s99, 0x360
	s_cbranch_scc1 .Lp0_join
	s_mul_hi_u32 s101, s99, 0x2aaaaab
	s_mul_i32 s24, s101, 0x60
	s_sub_u32 s24, s99, s24
	s_add_u32 s101, s101, 5
	s_lshl_b32 s101, s101, 9
	s_add_u32 s24, s24, s101
	s_sub_u32 s19, s24, s92
	s_mov_b32 s98, 0
